# MLA loops both layers: loop-carried K/V tile pointers instead of the per-step scalar address block, packed-f32 row sums (fewer instructions per step)
# baseline (speedup 1.0000x reference)
.LBB0_891:
	s_lshr_b32 s16, s19, 6
	s_and_b64 s[12:13], s[12:13], exec
	s_cselect_b32 s12, s19, s16
	s_and_b32 s17, s12, 7
	s_mul_i32 s12, s9, 0xc00
	s_mul_hi_u32 s13, s8, 0xc00
	s_add_i32 s13, s13, s12
	s_mul_i32 s12, s8, 0xc00
	v_readlane_b32 s20, v242, 21
	v_readlane_b32 s21, v242, 22
	s_add_u32 s12, s20, s12
	s_addc_u32 s13, s21, s13
	s_mul_i32 s16, s17, 0x180
	s_add_u32 s28, s12, s16
	s_addc_u32 s29, s13, 0
	s_mul_i32 s12, s1, 0xc00
	s_mul_hi_u32 s13, s0, 0xc00
	s_add_i32 s13, s13, s12
	s_mul_i32 s12, s0, 0xc00
	s_add_u32 s12, s27, s12
	s_addc_u32 s13, s30, s13
	s_add_u32 s12, s12, s16
	s_mul_i32 s20, s15, 0x3000000
	s_mul_hi_u32 s21, s14, 0x3000000
	s_addc_u32 s13, s13, 0
	s_add_i32 s21, s21, s20
	s_mul_i32 s20, s14, 0x3000000
	s_add_u32 s20, s27, s20
	s_addc_u32 s21, s30, s21
	s_add_u32 s22, s20, s16
	s_addc_u32 s23, s21, 0
	s_lshl_b64 s[0:1], s[0:1], 12
	s_add_u32 s0, s31, s0
	s_addc_u32 s1, s34, s1
	s_lshl_b32 s16, s17, 9
	s_add_u32 s0, s0, s16
	s_addc_u32 s1, s1, 0
	s_add_u32 s24, s0, 0x100
	s_addc_u32 s25, s1, 0
	s_lshl_b64 s[14:15], s[14:15], 26
	s_add_u32 s14, s31, s14
	s_addc_u32 s15, s34, s15
	s_add_u32 s14, s14, s16
	s_addc_u32 s15, s15, 0
	s_add_u32 s33, s14, 0x100
	v_readfirstlane_b32 s68, v0
	s_addc_u32 s35, s15, 0
	s_lshr_b32 s20, s68, 6
	s_lshl_b32 s16, s20, 5
	v_or_b32_e32 v4, s16, v1
	v_mov_b64_e32 v[2:3], s[28:29]
	s_movk_i32 s14, 0xc00
	v_mad_u64_u32 v[2:3], s[14:15], v4, s14, v[2:3]
	s_andn2_b32 s68, s68, 63
	v_lshl_add_u64 v[2:3], v[2:3], 0, v[148:149]
	global_load_dwordx4 v[142:145], v[2:3], off
	global_load_dwordx4 v[138:141], v[2:3], off offset:32
	global_load_dwordx4 v[134:137], v[2:3], off offset:64
	global_load_dwordx4 v[130:133], v[2:3], off offset:96
	global_load_dwordx4 v[126:129], v[2:3], off offset:128
	global_load_dwordx4 v[122:125], v[2:3], off offset:160
	global_load_dwordx4 v[118:121], v[2:3], off offset:192
	global_load_dwordx4 v[114:117], v[2:3], off offset:224
	global_load_dwordx4 v[110:113], v[2:3], off offset:256
	global_load_dwordx4 v[106:109], v[2:3], off offset:288
	global_load_dwordx4 v[102:105], v[2:3], off offset:320
	global_load_dwordx4 v[98:101], v[2:3], off offset:352
	v_or_b32_e32 v2, s68, v166
	v_mul_hi_i32 v3, v2, s11
	v_lshrrev_b32_e32 v4, 31, v3
	v_ashrrev_i32_e32 v3, 2, v3
	v_add_u32_e32 v3, v3, v4
	v_mul_lo_u32 v4, v3, 24
	v_sub_u32_e32 v4, v2, v4
	v_mul_lo_u32 v5, v3, s18
	v_lshrrev_b32_e32 v3, 1, v3
	v_bitop3_b32 v3, v3, v4, 7 bitop3:0x6c
	v_lshl_add_u32 v160, v3, 3, v5
	v_add_u32_e32 v3, 0x200, v2
	v_mul_hi_i32 v4, v3, s11
	v_lshrrev_b32_e32 v5, 31, v4
	v_ashrrev_i32_e32 v4, 2, v4
	v_add_u32_e32 v4, v4, v5
	v_mul_lo_u32 v5, v4, 24
	v_sub_u32_e32 v3, v3, v5
	v_mul_lo_u32 v5, v4, s18
	v_lshrrev_b32_e32 v4, 1, v4
	v_bitop3_b32 v3, v4, v3, 7 bitop3:0x6c
	v_lshl_add_u32 v162, v3, 3, v5
	v_add_u32_e32 v3, 0x400, v2
	v_mul_hi_i32 v4, v3, s11
	v_lshrrev_b32_e32 v5, 31, v4
	v_ashrrev_i32_e32 v4, 2, v4
	v_add_u32_e32 v4, v4, v5
	s_ashr_i32 s14, s68, 4
	v_mul_lo_u32 v5, v4, 24
	s_and_b32 s15, s14, 0x1ffff0
	s_lshr_b32 s14, s14, 1
	v_sub_u32_e32 v3, v3, v5
	v_mul_lo_u32 v5, v4, s18
	v_lshrrev_b32_e32 v4, 1, v4
	s_and_b32 s14, s14, 4
	v_bitop3_b32 v3, v4, v3, 7 bitop3:0x6c
	s_or_b32 s14, s15, s14
	v_lshl_add_u32 v170, v3, 3, v5
	v_or_b32_e32 v3, s14, v169
	s_add_i32 s14, s68, 0x200
	s_ashr_i32 s14, s14, 4
	s_and_b32 s15, s14, 0x1ffff0
	s_lshr_b32 s14, s14, 1
	s_and_b32 s14, s14, 4
	v_and_or_b32 v2, v2, s10, v165
	s_or_b32 s14, s15, s14
	v_lshl_or_b32 v172, v3, 11, v2
	v_or_b32_e32 v3, s14, v169
	s_lshl_b32 s14, s20, 10
	s_add_i32 s69, s14, 0
	v_ashrrev_i32_e32 v161, 31, v160
	v_lshl_or_b32 v174, v3, 11, v2
	s_add_i32 m0, s69, 0x8000
	v_lshl_add_u64 v[2:3], v[160:161], 1, s[12:13]
	v_ashrrev_i32_e32 v163, 31, v162
	global_load_lds_dwordx4 v[2:3], off
	v_lshl_add_u64 v[2:3], v[162:163], 1, s[12:13]
	s_add_i32 m0, s69, 0xa000
	v_ashrrev_i32_e32 v171, 31, v170
	global_load_lds_dwordx4 v[2:3], off
	v_lshl_add_u64 v[2:3], v[170:171], 1, s[12:13]
	s_add_i32 m0, s69, 0xc000
	v_ashrrev_i32_e32 v173, 31, v172
	global_load_lds_dwordx4 v[2:3], off
	v_lshl_add_u64 v[2:3], v[172:173], 1, s[0:1]
	v_lshl_add_u64 v[2:3], v[2:3], 0, s[6:7]
	s_mov_b32 m0, s69
	v_ashrrev_i32_e32 v175, 31, v174
	global_load_lds_dwordx4 v[2:3], off
	v_lshl_add_u64 v[2:3], v[174:175], 1, s[0:1]
	v_lshl_add_u64 v[2:3], v[2:3], 0, s[6:7]
	s_add_i32 m0, s69, 0x2000
	v_mov_b32_e32 v151, 0
	global_load_lds_dwordx4 v[2:3], off
	s_waitcnt vmcnt(0)
	s_add_i32 s0, s4, 1
	s_mov_b32 s4, 0
	s_mov_b64 s[14:15], 64
	v_mov_b32_e32 v2, 0
	v_mov_b32_e32 v3, v151
	v_mov_b32_e32 v4, v151
	v_mov_b32_e32 v5, v151
	v_mov_b32_e32 v6, v151
	v_mov_b32_e32 v7, v151
	v_mov_b32_e32 v8, v151
	v_mov_b32_e32 v9, v151
	v_mov_b32_e32 v10, v151
	v_mov_b32_e32 v11, v151
	v_mov_b32_e32 v12, v151
	v_mov_b32_e32 v13, v151
	v_mov_b32_e32 v14, v151
	v_mov_b32_e32 v15, v151
	v_mov_b32_e32 v16, v151
	v_mov_b32_e32 v17, v151
	v_mov_b32_e32 v18, 0
	v_mov_b32_e32 v19, v151
	v_mov_b32_e32 v20, v151
	v_mov_b32_e32 v21, v151
	v_mov_b32_e32 v22, v151
	v_mov_b32_e32 v23, v151
	v_mov_b32_e32 v24, v151
	v_mov_b32_e32 v25, v151
	v_mov_b32_e32 v26, v151
	v_mov_b32_e32 v27, v151
	v_mov_b32_e32 v28, v151
	v_mov_b32_e32 v29, v151
	v_mov_b32_e32 v30, v151
	v_mov_b32_e32 v31, v151
	v_mov_b32_e32 v32, v151
	v_mov_b32_e32 v33, v151
	v_mov_b32_e32 v34, 0
	v_mov_b32_e32 v35, v151
	v_mov_b32_e32 v36, v151
	v_mov_b32_e32 v37, v151
	v_mov_b32_e32 v38, v151
	v_mov_b32_e32 v39, v151
	v_mov_b32_e32 v40, v151
	v_mov_b32_e32 v41, v151
	v_mov_b32_e32 v42, v151
	v_mov_b32_e32 v43, v151
	v_mov_b32_e32 v44, v151
	v_mov_b32_e32 v45, v151
	v_mov_b32_e32 v46, v151
	v_mov_b32_e32 v47, v151
	v_mov_b32_e32 v48, v151
	v_mov_b32_e32 v49, v151
	v_mov_b32_e32 v50, 0
	v_mov_b32_e32 v51, v151
	v_mov_b32_e32 v52, v151
	v_mov_b32_e32 v53, v151
	v_mov_b32_e32 v54, v151
	v_mov_b32_e32 v55, v151
	v_mov_b32_e32 v56, v151
	v_mov_b32_e32 v57, v151
	v_mov_b32_e32 v58, v151
	v_mov_b32_e32 v59, v151
	v_mov_b32_e32 v60, v151
	v_mov_b32_e32 v61, v151
	v_mov_b32_e32 v62, v151
	v_mov_b32_e32 v63, v151
	v_mov_b32_e32 v64, v151
	v_mov_b32_e32 v65, v151
	s_waitcnt vmcnt(0) lgkmcnt(0)
	s_barrier
	s_add_u32 s38, s12, 0x30000
	s_addc_u32 s39, s13, 0
	s_add_u32 s28, s24, 0x40000
	s_addc_u32 s29, s25, 0
	s_mov_b32 s98, 0
	s_mov_b32 s99, 0
	s_branch .LBB0_892
.Lmla0_sw:
	s_mov_b32 s38, s22
	s_mov_b32 s39, s23
	s_mov_b32 s28, s33
	s_mov_b32 s29, s35
	s_branch .Lmla0_swr
.LBB0_892:
	s_add_i32 s1, s4, 1
	s_xor_b32 s36, s99, 0x6000
	s_add_i32 s36, s69, s36
	s_add_i32 m0, s36, 0x8000
	v_lshl_add_u64 v[66:67], v[160:161], 1, s[38:39]
	global_load_lds_dwordx4 v[66:67], off
	s_add_i32 m0, s36, 0xa000
	v_lshl_add_u64 v[66:67], v[162:163], 1, s[38:39]
	global_load_lds_dwordx4 v[66:67], off
	s_add_i32 m0, s36, 0xc000
	v_lshl_add_u64 v[66:67], v[170:171], 1, s[38:39]
	global_load_lds_dwordx4 v[66:67], off
	s_xor_b32 s36, s98, 0x4000
	s_add_i32 s36, s69, s36
	s_mov_b32 m0, s36
	v_lshl_add_u64 v[66:67], v[172:173], 1, s[28:29]
	global_load_lds_dwordx4 v[66:67], off
	s_add_i32 m0, s36, 0x2000
	v_lshl_add_u64 v[66:67], v[174:175], 1, s[28:29]
	global_load_lds_dwordx4 v[66:67], off
	s_add_u32 s38, s38, 0x30000
	s_addc_u32 s39, s39, 0
	s_add_u32 s28, s28, 0x40000
	s_addc_u32 s29, s29, 0
	s_cmp_eq_u32 s1, 3
	s_cbranch_scc1 .Lmla0_sw
	.Lmla0_swr:
	v_add_u32_e32 v70, s99, v179
	v_add_u32_e32 v71, v70, v178
	ds_read_b128 v[66:69], v71 offset:32768
	v_add_u32_e32 v153, v70, v180
	v_add_u32_e32 v155, v70, v181
	v_add_u32_e32 v157, v70, v182
	v_add_u32_e32 v159, v70, v183
	v_add_u32_e32 v193, v70, v184
	v_add_u32_e32 v198, v70, v185
	v_add_u32_e32 v199, v70, v186
	v_add_u32_e32 v200, v70, v187
	s_waitcnt lgkmcnt(0)
	v_mfma_f32_32x32x16_bf16 v[82:97], v[66:69], v[142:145], 0
	ds_read_b128 v[66:69], v153 offset:32768
	v_add_u32_e32 v201, v70, v188
	v_add_u32_e32 v202, v70, v189
	v_add_u32_e32 v203, v70, v190
	s_waitcnt lgkmcnt(0)
	v_mfma_f32_32x32x16_bf16 v[82:97], v[66:69], v[138:141], v[82:97]
	ds_read_b128 v[66:69], v155 offset:32768
	s_waitcnt lgkmcnt(0)
	v_mfma_f32_32x32x16_bf16 v[82:97], v[66:69], v[134:137], v[82:97]
	ds_read_b128 v[66:69], v157 offset:32768
	s_waitcnt lgkmcnt(0)
	v_mfma_f32_32x32x16_bf16 v[82:97], v[66:69], v[130:133], v[82:97]
	ds_read_b128 v[66:69], v159 offset:32768
	s_waitcnt lgkmcnt(0)
	v_mfma_f32_32x32x16_bf16 v[82:97], v[66:69], v[126:129], v[82:97]
	ds_read_b128 v[66:69], v193 offset:32768
	s_waitcnt lgkmcnt(0)
	v_mfma_f32_32x32x16_bf16 v[82:97], v[66:69], v[122:125], v[82:97]
	ds_read_b128 v[66:69], v198 offset:32768
	s_waitcnt lgkmcnt(0)
	v_mfma_f32_32x32x16_bf16 v[82:97], v[66:69], v[118:121], v[82:97]
	ds_read_b128 v[66:69], v199 offset:32768
	s_waitcnt lgkmcnt(0)
	v_mfma_f32_32x32x16_bf16 v[82:97], v[66:69], v[114:117], v[82:97]
	ds_read_b128 v[66:69], v200 offset:32768
	s_waitcnt lgkmcnt(0)
	v_mfma_f32_32x32x16_bf16 v[82:97], v[66:69], v[110:113], v[82:97]
	ds_read_b128 v[66:69], v201 offset:32768
	s_waitcnt lgkmcnt(0)
	v_mfma_f32_32x32x16_bf16 v[82:97], v[66:69], v[106:109], v[82:97]
	ds_read_b128 v[66:69], v202 offset:32768
	s_waitcnt lgkmcnt(0)
	v_mfma_f32_32x32x16_bf16 v[82:97], v[66:69], v[102:105], v[82:97]
	ds_read_b128 v[66:69], v203 offset:32768
	s_waitcnt lgkmcnt(0)
	v_mfma_f32_32x32x16_bf16 v[82:97], v[66:69], v[98:101], v[82:97]
	ds_read_b128 v[66:69], v71 offset:45056
	ds_read_b128 v[194:197], v153 offset:45056
	s_nop 9
	v_exp_f32_e32 v204, v88
	v_exp_f32_e32 v205, v89
	v_exp_f32_e32 v206, v90
	v_exp_f32_e32 v207, v91
	v_exp_f32_e32 v208, v92
	v_exp_f32_e32 v209, v93
	v_exp_f32_e32 v210, v94
	s_waitcnt lgkmcnt(0)
	v_mfma_f32_32x32x16_bf16 v[66:81], v[66:69], v[142:145], 0
	v_exp_f32_e32 v211, v95
	v_exp_f32_e32 v212, v96
	v_exp_f32_e32 v213, v97
	v_add_u32_e32 v153, s98, v176
	v_cvt_pk_bf16_f32 v88, v210, v211
	v_cvt_pk_bf16_f32 v89, v212, v213
	v_mfma_f32_32x32x16_bf16 v[66:81], v[194:197], v[138:141], v[66:81]
	ds_read_b128 v[194:197], v155 offset:45056
	v_exp_f32_e32 v218, v82
	s_waitcnt lgkmcnt(0)
	v_mfma_f32_32x32x16_bf16 v[66:81], v[194:197], v[134:137], v[66:81]
	ds_read_b128 v[194:197], v157 offset:45056
	v_exp_f32_e32 v219, v83
	s_nop 0
	v_cvt_pk_bf16_f32 v82, v218, v219
	s_waitcnt lgkmcnt(0)
	v_mfma_f32_32x32x16_bf16 v[66:81], v[194:197], v[130:133], v[66:81]
	ds_read_b128 v[194:197], v159 offset:45056
	v_exp_f32_e32 v220, v84
	s_waitcnt lgkmcnt(0)
	v_mfma_f32_32x32x16_bf16 v[66:81], v[194:197], v[126:129], v[66:81]
	ds_read_b128 v[194:197], v193 offset:45056
	v_exp_f32_e32 v221, v85
	v_cvt_pk_bf16_f32 v85, v204, v205
	v_cvt_pk_bf16_f32 v83, v220, v221
	s_nop 1
	v_permlane32_swap_b32_e32 v83, v85
	s_waitcnt lgkmcnt(0)
	v_mfma_f32_32x32x16_bf16 v[66:81], v[194:197], v[122:125], v[66:81]
	ds_read_b128 v[194:197], v198 offset:45056
	s_waitcnt lgkmcnt(0)
	v_mfma_f32_32x32x16_bf16 v[66:81], v[194:197], v[118:121], v[66:81]
	ds_read_b128 v[194:197], v199 offset:45056
	s_waitcnt lgkmcnt(0)
	v_mfma_f32_32x32x16_bf16 v[66:81], v[194:197], v[114:117], v[66:81]
	ds_read_b128 v[194:197], v200 offset:45056
	s_waitcnt lgkmcnt(0)
	v_mfma_f32_32x32x16_bf16 v[66:81], v[194:197], v[110:113], v[66:81]
	ds_read_b128 v[194:197], v201 offset:45056
	s_waitcnt lgkmcnt(0)
	v_mfma_f32_32x32x16_bf16 v[66:81], v[194:197], v[106:109], v[66:81]
	ds_read_b128 v[194:197], v202 offset:45056
	v_exp_f32_e32 v202, v86
	v_cvt_pk_bf16_f32 v86, v206, v207
	s_nop 1
	v_permlane32_swap_b32_e32 v86, v88
	s_waitcnt lgkmcnt(0)
	v_mfma_f32_32x32x16_bf16 v[66:81], v[194:197], v[102:105], v[66:81]
	ds_read_b128 v[194:197], v203 offset:45056
	v_exp_f32_e32 v203, v87
	v_cvt_pk_bf16_f32 v87, v208, v209
	s_nop 1
	v_permlane32_swap_b32_e32 v87, v89
	v_cvt_pk_bf16_f32 v84, v202, v203
	s_nop 1
	v_permlane32_swap_b32_e32 v82, v84
	s_waitcnt lgkmcnt(0)
	v_mfma_f32_32x32x16_bf16 v[66:81], v[194:197], v[98:101], v[66:81]
	ds_read_b64_tr_b16 v[90:91], v153 offset:0
	ds_read_b64_tr_b16 v[92:93], v153 offset:0x800
	ds_read_b64_tr_b16 v[94:95], v153 offset:0x1000
	ds_read_b64_tr_b16 v[96:97], v153 offset:0x1800
	ds_read_b64_tr_b16 v[194:195], v153 offset:0x200
	ds_read_b64_tr_b16 v[196:197], v153 offset:0xa00
	ds_read_b64_tr_b16 v[198:199], v153 offset:0x1200
	ds_read_b64_tr_b16 v[200:201], v153 offset:0x1a00
	s_waitcnt lgkmcnt(4)
	s_nop 0
	v_mfma_f32_32x32x16_bf16 v[2:17], v[82:85], v[90:93], v[2:17]
	s_nop 9
	v_exp_f32_e32 v214, v66
	v_exp_f32_e32 v215, v67
	v_exp_f32_e32 v216, v68
	v_exp_f32_e32 v217, v69
	v_mfma_f32_32x32x16_bf16 v[2:17], v[86:89], v[94:97], v[2:17]
	ds_read_b64_tr_b16 v[66:67], v153 offset:0x400
	ds_read_b64_tr_b16 v[68:69], v153 offset:0xc00
	ds_read_b64_tr_b16 v[90:91], v153 offset:0x1400
	ds_read_b64_tr_b16 v[92:93], v153 offset:0x1c00
	s_waitcnt lgkmcnt(4)
	v_mfma_f32_32x32x16_bf16 v[18:33], v[82:85], v[194:197], v[18:33]
	v_exp_f32_e32 v194, v70
	v_exp_f32_e32 v195, v71
	v_exp_f32_e32 v196, v72
	v_exp_f32_e32 v197, v73
	v_mfma_f32_32x32x16_bf16 v[18:33], v[86:89], v[198:201], v[18:33]
	ds_read_b64_tr_b16 v[70:71], v153 offset:0x600
	ds_read_b64_tr_b16 v[72:73], v153 offset:0xe00
	ds_read_b64_tr_b16 v[94:95], v153 offset:0x1600
	ds_read_b64_tr_b16 v[96:97], v153 offset:0x1e00
	s_waitcnt lgkmcnt(4)
	v_mfma_f32_32x32x16_bf16 v[34:49], v[82:85], v[66:69], v[34:49]
	v_exp_f32_e32 v198, v74
	v_exp_f32_e32 v199, v75
	v_exp_f32_e32 v200, v76
	v_exp_f32_e32 v201, v77
	v_mfma_f32_32x32x16_bf16 v[34:49], v[86:89], v[90:93], v[34:49]
	ds_read_b64_tr_b16 v[66:67], v153 offset:0x2000
	ds_read_b64_tr_b16 v[68:69], v153 offset:0x2800
	ds_read_b64_tr_b16 v[74:75], v153 offset:0x3000
	ds_read_b64_tr_b16 v[76:77], v153 offset:0x3800
	s_waitcnt lgkmcnt(4)
	v_mfma_f32_32x32x16_bf16 v[50:65], v[82:85], v[70:73], v[50:65]
	v_exp_f32_e32 v249, v78
	v_exp_f32_e32 v250, v79
	v_cvt_pk_bf16_f32 v72, v194, v195
	v_cvt_pk_bf16_f32 v73, v196, v197
	v_mfma_f32_32x32x16_bf16 v[50:65], v[86:89], v[94:97], v[50:65]
	v_exp_f32_e32 v251, v80
	v_exp_f32_e32 v248, v81
	v_cvt_pk_bf16_f32 v78, v198, v199
	v_cvt_pk_bf16_f32 v79, v200, v201
	v_cvt_pk_bf16_f32 v80, v249, v250
	v_cvt_pk_bf16_f32 v70, v214, v215
	v_cvt_pk_bf16_f32 v71, v216, v217
	v_permlane32_swap_b32_e32 v78, v80
	v_cvt_pk_bf16_f32 v81, v251, v248
	v_permlane32_swap_b32_e32 v70, v72
	v_permlane32_swap_b32_e32 v71, v73
	s_nop 0
	v_permlane32_swap_b32_e32 v79, v81
	ds_read_b64_tr_b16 v[82:83], v153 offset:0x2200
	ds_read_b64_tr_b16 v[84:85], v153 offset:0x2a00
	ds_read_b64_tr_b16 v[86:87], v153 offset:0x3200
	ds_read_b64_tr_b16 v[88:89], v153 offset:0x3a00
	s_waitcnt lgkmcnt(4)
	s_nop 0
	v_mfma_f32_32x32x16_bf16 v[2:17], v[70:73], v[66:69], v[2:17]
	v_pk_add_f32 v[246:247], v[218:219], v[220:221]
	v_pk_add_f32 v[246:247], v[246:247], v[202:203]
	v_mfma_f32_32x32x16_bf16 v[2:17], v[78:81], v[74:77], v[2:17]
	v_pk_add_f32 v[246:247], v[246:247], v[204:205]
	v_pk_add_f32 v[246:247], v[246:247], v[206:207]
	ds_read_b64_tr_b16 v[66:67], v153 offset:0x2400
	ds_read_b64_tr_b16 v[68:69], v153 offset:0x2c00
	ds_read_b64_tr_b16 v[74:75], v153 offset:0x3400
	ds_read_b64_tr_b16 v[76:77], v153 offset:0x3c00
	s_waitcnt lgkmcnt(4)
	v_mfma_f32_32x32x16_bf16 v[18:33], v[70:73], v[82:85], v[18:33]
	v_pk_add_f32 v[246:247], v[246:247], v[208:209]
	v_pk_add_f32 v[246:247], v[246:247], v[210:211]
	v_mfma_f32_32x32x16_bf16 v[18:33], v[78:81], v[86:89], v[18:33]
	v_pk_add_f32 v[246:247], v[246:247], v[212:213]
	v_pk_add_f32 v[246:247], v[246:247], v[214:215]
	ds_read_b64_tr_b16 v[82:83], v153 offset:0x2600
	ds_read_b64_tr_b16 v[84:85], v153 offset:0x2e00
	ds_read_b64_tr_b16 v[86:87], v153 offset:0x3600
	ds_read_b64_tr_b16 v[88:89], v153 offset:0x3e00
	s_waitcnt lgkmcnt(4)
	v_mfma_f32_32x32x16_bf16 v[34:49], v[70:73], v[66:69], v[34:49]
	v_pk_add_f32 v[246:247], v[246:247], v[216:217]
	v_pk_add_f32 v[246:247], v[246:247], v[194:195]
	v_mfma_f32_32x32x16_bf16 v[34:49], v[78:81], v[74:77], v[34:49]
	v_pk_add_f32 v[246:247], v[246:247], v[196:197]
	v_pk_add_f32 v[246:247], v[246:247], v[198:199]
	s_waitcnt lgkmcnt(0)
	v_mfma_f32_32x32x16_bf16 v[50:65], v[70:73], v[82:85], v[50:65]
	v_pk_add_f32 v[246:247], v[246:247], v[200:201]
	v_pk_add_f32 v[246:247], v[246:247], v[248:249]
	v_pk_add_f32 v[246:247], v[246:247], v[250:251]
	v_add_f32_e32 v246, v246, v247
	v_mov_b32_e32 v247, v246
	s_nop 1
	v_permlane32_swap_b32_e32 v246, v247
	v_add_f32_e32 v246, v246, v247
	v_add_f32_e32 v151, v151, v246
	s_waitcnt vmcnt(0)
	s_xor_b32 s99, s99, 0x6000
	s_xor_b32 s98, s98, 0x4000
	s_cmp_eq_u32 s0, s1
	s_mov_b32 s4, s1
	s_waitcnt vmcnt(0)
	s_barrier
	v_mfma_f32_32x32x16_bf16 v[50:65], v[78:81], v[86:89], v[50:65]
	s_cbranch_scc0 .LBB0_892
	s_lshl_b32 s1, s68, 2
	s_add_i32 s4, s1, 0
	s_and_b32 s0, s0, 1
	s_add_i32 s4, s4, 0x1e000
	s_mul_i32 s1, s0, 0x6000
	v_add_u32_e32 v70, s1, v179
	v_add_u32_e32 v71, v70, v178
	ds_read_b128 v[66:69], v71 offset:32768
	v_add_u32_e32 v153, v70, v180
	v_add_u32_e32 v155, v70, v181
	v_add_u32_e32 v157, v70, v182
	v_add_u32_e32 v159, v70, v183
	v_add_u32_e32 v160, v70, v184
	v_add_u32_e32 v161, v70, v185
	v_add_u32_e32 v162, v70, v186
	v_add_u32_e32 v163, v70, v187
	s_waitcnt lgkmcnt(0)
	v_mfma_f32_32x32x16_bf16 v[82:97], v[66:69], v[142:145], 0
	ds_read_b128 v[66:69], v153 offset:32768
	v_add_u32_e32 v170, v70, v188
	v_add_u32_e32 v171, v70, v189
	v_add_u32_e32 v172, v70, v190
	s_waitcnt lgkmcnt(0)
	v_mfma_f32_32x32x16_bf16 v[82:97], v[66:69], v[138:141], v[82:97]
	ds_read_b128 v[66:69], v155 offset:32768
	s_waitcnt lgkmcnt(0)
	v_mfma_f32_32x32x16_bf16 v[82:97], v[66:69], v[134:137], v[82:97]
	ds_read_b128 v[66:69], v157 offset:32768
	s_waitcnt lgkmcnt(0)
	v_mfma_f32_32x32x16_bf16 v[82:97], v[66:69], v[130:133], v[82:97]
	ds_read_b128 v[66:69], v159 offset:32768
	s_waitcnt lgkmcnt(0)
	v_mfma_f32_32x32x16_bf16 v[82:97], v[66:69], v[126:129], v[82:97]
	ds_read_b128 v[66:69], v160 offset:32768
	s_waitcnt lgkmcnt(0)
	v_mfma_f32_32x32x16_bf16 v[82:97], v[66:69], v[122:125], v[82:97]
	ds_read_b128 v[66:69], v161 offset:32768
	s_waitcnt lgkmcnt(0)
	v_mfma_f32_32x32x16_bf16 v[82:97], v[66:69], v[118:121], v[82:97]
	ds_read_b128 v[66:69], v162 offset:32768
	s_waitcnt lgkmcnt(0)
	v_mfma_f32_32x32x16_bf16 v[82:97], v[66:69], v[114:117], v[82:97]
	ds_read_b128 v[66:69], v163 offset:32768
	s_waitcnt lgkmcnt(0)
	v_mfma_f32_32x32x16_bf16 v[82:97], v[66:69], v[110:113], v[82:97]
	ds_read_b128 v[66:69], v170 offset:32768
	s_waitcnt lgkmcnt(0)
	v_mfma_f32_32x32x16_bf16 v[82:97], v[66:69], v[106:109], v[82:97]
	ds_read_b128 v[66:69], v171 offset:32768
	s_waitcnt lgkmcnt(0)
	v_mfma_f32_32x32x16_bf16 v[82:97], v[66:69], v[102:105], v[82:97]
	ds_read_b128 v[66:69], v172 offset:32768
	s_waitcnt lgkmcnt(0)
	v_mfma_f32_32x32x16_bf16 v[82:97], v[66:69], v[98:101], v[82:97]
	ds_read_b128 v[66:69], v71 offset:45056
	s_waitcnt lgkmcnt(0)
	v_mfma_f32_32x32x16_bf16 v[66:81], v[66:69], v[142:145], 0
	ds_read_b128 v[142:145], v153 offset:45056
	s_waitcnt lgkmcnt(0)
	v_mfma_f32_32x32x16_bf16 v[66:81], v[142:145], v[138:141], v[66:81]
	ds_read_b128 v[138:141], v155 offset:45056
	s_waitcnt lgkmcnt(0)
	v_mfma_f32_32x32x16_bf16 v[66:81], v[138:141], v[134:137], v[66:81]
	ds_read_b128 v[134:137], v157 offset:45056
	s_waitcnt lgkmcnt(0)
	v_mfma_f32_32x32x16_bf16 v[66:81], v[134:137], v[130:133], v[66:81]
	ds_read_b128 v[130:133], v159 offset:45056
	s_waitcnt lgkmcnt(0)
	v_mfma_f32_32x32x16_bf16 v[66:81], v[130:133], v[126:129], v[66:81]
	ds_read_b128 v[126:129], v160 offset:45056
	s_waitcnt lgkmcnt(0)
	v_mfma_f32_32x32x16_bf16 v[66:81], v[126:129], v[122:125], v[66:81]
	ds_read_b128 v[122:125], v161 offset:45056
	s_waitcnt lgkmcnt(0)
	v_mfma_f32_32x32x16_bf16 v[66:81], v[122:125], v[118:121], v[66:81]
	ds_read_b128 v[118:121], v162 offset:45056
	v_exp_f32_e32 v122, v97
	s_waitcnt lgkmcnt(0)
	v_mfma_f32_32x32x16_bf16 v[66:81], v[118:121], v[114:117], v[66:81]
	ds_read_b128 v[114:117], v163 offset:45056
	v_exp_f32_e32 v118, v93
	v_exp_f32_e32 v119, v94
	v_exp_f32_e32 v120, v95
	v_exp_f32_e32 v121, v96
	s_waitcnt lgkmcnt(0)
	v_mfma_f32_32x32x16_bf16 v[66:81], v[114:117], v[110:113], v[66:81]
	ds_read_b128 v[110:113], v170 offset:45056
	v_exp_f32_e32 v114, v89
	v_exp_f32_e32 v115, v90
	v_exp_f32_e32 v116, v91
	v_exp_f32_e32 v117, v92
	v_cvt_pk_bf16_f32 v89, v121, v122
	s_waitcnt lgkmcnt(0)
	v_mfma_f32_32x32x16_bf16 v[66:81], v[110:113], v[106:109], v[66:81]
	ds_read_b128 v[106:109], v171 offset:45056
	v_exp_f32_e32 v110, v85
	v_exp_f32_e32 v111, v86
	v_exp_f32_e32 v112, v87
	v_exp_f32_e32 v113, v88
	v_cvt_pk_bf16_f32 v86, v115, v116
	v_cvt_pk_bf16_f32 v87, v117, v118
	s_waitcnt lgkmcnt(0)
	v_mfma_f32_32x32x16_bf16 v[66:81], v[106:109], v[102:105], v[66:81]
	ds_read_b128 v[102:105], v172 offset:45056
	v_exp_f32_e32 v107, v82
	v_exp_f32_e32 v108, v83
	v_exp_f32_e32 v109, v84
	v_cvt_pk_bf16_f32 v84, v111, v112
	v_cvt_pk_bf16_f32 v85, v113, v114
	v_cvt_pk_bf16_f32 v82, v107, v108
	s_waitcnt lgkmcnt(0)
	v_mfma_f32_32x32x16_bf16 v[66:81], v[102:105], v[98:101], v[66:81]
	v_cvt_pk_bf16_f32 v83, v109, v110
	v_cvt_pk_bf16_f32 v88, v119, v120
	v_lshl_add_u32 v106, s0, 14, v176
	v_permlane32_swap_b32_e32 v82, v84
	v_permlane32_swap_b32_e32 v83, v85
	v_permlane32_swap_b32_e32 v86, v88
	v_permlane32_swap_b32_e32 v87, v89
	ds_read_b64_tr_b16 v[90:91], v106 offset:0
	ds_read_b64_tr_b16 v[92:93], v106 offset:0x800
	ds_read_b64_tr_b16 v[94:95], v106 offset:0x1000
	ds_read_b64_tr_b16 v[96:97], v106 offset:0x1800
	ds_read_b64_tr_b16 v[98:99], v106 offset:0x200
	ds_read_b64_tr_b16 v[100:101], v106 offset:0xa00
	ds_read_b64_tr_b16 v[102:103], v106 offset:0x1200
	ds_read_b64_tr_b16 v[104:105], v106 offset:0x1a00
	s_waitcnt lgkmcnt(4)
	s_nop 0
	v_mfma_f32_32x32x16_bf16 v[2:17], v[82:85], v[90:93], v[2:17]
	s_nop 2
	v_exp_f32_e32 v123, v66
	v_exp_f32_e32 v124, v67
	v_exp_f32_e32 v125, v68
	v_exp_f32_e32 v126, v69
	v_mfma_f32_32x32x16_bf16 v[2:17], v[86:89], v[94:97], v[2:17]
	ds_read_b64_tr_b16 v[66:67], v106 offset:0x400
	ds_read_b64_tr_b16 v[68:69], v106 offset:0xc00
	ds_read_b64_tr_b16 v[90:91], v106 offset:0x1400
	ds_read_b64_tr_b16 v[92:93], v106 offset:0x1c00
	s_waitcnt lgkmcnt(4)
	v_mfma_f32_32x32x16_bf16 v[18:33], v[82:85], v[98:101], v[18:33]
	v_exp_f32_e32 v98, v70
	v_exp_f32_e32 v99, v71
	v_exp_f32_e32 v100, v72
	v_exp_f32_e32 v101, v73
	v_mfma_f32_32x32x16_bf16 v[18:33], v[86:89], v[102:105], v[18:33]
	ds_read_b64_tr_b16 v[70:71], v106 offset:0x600
	ds_read_b64_tr_b16 v[72:73], v106 offset:0xe00
	ds_read_b64_tr_b16 v[94:95], v106 offset:0x1600
	ds_read_b64_tr_b16 v[96:97], v106 offset:0x1e00
	s_waitcnt lgkmcnt(4)
	v_mfma_f32_32x32x16_bf16 v[34:49], v[82:85], v[66:69], v[34:49]
	v_exp_f32_e32 v102, v74
	v_exp_f32_e32 v103, v75
	v_exp_f32_e32 v104, v76
	v_exp_f32_e32 v105, v77
	v_mfma_f32_32x32x16_bf16 v[34:49], v[86:89], v[90:93], v[34:49]
	ds_read_b64_tr_b16 v[74:75], v106 offset:0x2000
	ds_read_b64_tr_b16 v[76:77], v106 offset:0x2800
	ds_read_b64_tr_b16 v[90:91], v106 offset:0x3000
	ds_read_b64_tr_b16 v[92:93], v106 offset:0x3800
	s_waitcnt lgkmcnt(4)
	v_add_f32_e32 v66, v107, v108
	v_add_f32_e32 v67, v123, v124
	v_mfma_f32_32x32x16_bf16 v[50:65], v[82:85], v[70:73], v[50:65]
	v_add_f32_e32 v66, v66, v109
	v_add_f32_e32 v67, v67, v125
	v_exp_f32_e32 v127, v78
	v_add_f32_e32 v66, v66, v110
	v_add_f32_e32 v67, v67, v126
	v_exp_f32_e32 v128, v79
	v_add_f32_e32 v66, v66, v111
	v_add_f32_e32 v67, v67, v98
	v_mfma_f32_32x32x16_bf16 v[50:65], v[86:89], v[94:97], v[50:65]
	v_add_f32_e32 v66, v66, v112
	v_add_f32_e32 v67, v67, v99
	v_exp_f32_e32 v129, v80
	v_add_f32_e32 v66, v66, v113
	v_add_f32_e32 v67, v67, v100
	v_exp_f32_e32 v81, v81
	v_add_f32_e32 v66, v66, v114
	v_add_f32_e32 v67, v67, v101
	v_cvt_pk_bf16_f32 v68, v123, v124
	v_add_f32_e32 v66, v66, v115
	v_add_f32_e32 v67, v67, v102
	v_cvt_pk_bf16_f32 v69, v125, v126
	v_add_f32_e32 v66, v66, v116
	v_add_f32_e32 v67, v67, v103
	v_cvt_pk_bf16_f32 v70, v98, v99
	v_add_f32_e32 v66, v66, v117
	v_add_f32_e32 v67, v67, v104
	v_cvt_pk_bf16_f32 v71, v100, v101
	v_add_f32_e32 v66, v66, v118
	v_add_f32_e32 v67, v67, v105
	v_cvt_pk_bf16_f32 v78, v102, v103
	v_add_f32_e32 v66, v66, v119
	v_add_f32_e32 v67, v67, v127
	v_cvt_pk_bf16_f32 v79, v104, v105
	v_add_f32_e32 v66, v66, v120
	v_add_f32_e32 v67, v67, v128
	v_cvt_pk_bf16_f32 v80, v127, v128
	v_add_f32_e32 v66, v66, v121
	v_add_f32_e32 v67, v67, v129
	v_permlane32_swap_b32_e32 v68, v70
	v_add_f32_e32 v66, v66, v122
	v_add_f32_e32 v67, v67, v81
	v_cvt_pk_bf16_f32 v81, v129, v81
	v_add_f32_e32 v66, v66, v67
	v_mov_b32_e32 v67, v66
	s_nop 1
	v_permlane32_swap_b32_e32 v66, v67
	v_permlane32_swap_b32_e32 v69, v71
	v_permlane32_swap_b32_e32 v78, v80
	v_permlane32_swap_b32_e32 v79, v81
	ds_read_b64_tr_b16 v[82:83], v106 offset:0x2200
	ds_read_b64_tr_b16 v[84:85], v106 offset:0x2a00
	ds_read_b64_tr_b16 v[86:87], v106 offset:0x3200
	ds_read_b64_tr_b16 v[88:89], v106 offset:0x3a00
	s_waitcnt lgkmcnt(4)
	v_mfma_f32_32x32x16_bf16 v[2:17], v[68:71], v[74:77], v[2:17]
	s_nop 0
	v_mfma_f32_32x32x16_bf16 v[2:17], v[78:81], v[90:93], v[2:17]
	ds_read_b64_tr_b16 v[72:73], v106 offset:0x2400
	ds_read_b64_tr_b16 v[74:75], v106 offset:0x2c00
	ds_read_b64_tr_b16 v[90:91], v106 offset:0x3400
	ds_read_b64_tr_b16 v[92:93], v106 offset:0x3c00
	s_waitcnt lgkmcnt(4)
	v_mfma_f32_32x32x16_bf16 v[18:33], v[68:71], v[82:85], v[18:33]
	v_mfma_f32_32x32x16_bf16 v[18:33], v[78:81], v[86:89], v[18:33]
	ds_read_b64_tr_b16 v[82:83], v106 offset:0x2600
	ds_read_b64_tr_b16 v[84:85], v106 offset:0x2e00
	ds_read_b64_tr_b16 v[86:87], v106 offset:0x3600
	ds_read_b64_tr_b16 v[88:89], v106 offset:0x3e00
	s_waitcnt lgkmcnt(4)
	v_mfma_f32_32x32x16_bf16 v[34:49], v[68:71], v[72:75], v[34:49]
	v_mfma_f32_32x32x16_bf16 v[34:49], v[78:81], v[90:93], v[34:49]
	s_waitcnt lgkmcnt(0)
	v_mfma_f32_32x32x16_bf16 v[50:65], v[68:71], v[82:85], v[50:65]
	s_waitcnt vmcnt(0)
	s_barrier
	v_mfma_f32_32x32x16_bf16 v[50:65], v[78:81], v[86:89], v[50:65]
	s_and_saveexec_b64 s[0:1], s[2:3]
	s_cbranch_execz .LBB0_886
	v_add_f32_e32 v66, v66, v67
	v_lshl_add_u32 v68, v1, 2, s4
	v_add_f32_e32 v66, v151, v66
	ds_write_b32 v68, v66
	s_branch .LBB0_886

.LBB0_2311:
	s_ashr_i32 s14, s33, 9
	s_ashr_i32 s15, s14, 31
	s_lshl_b32 s0, s33, 8
	s_lshl_b64 s[8:9], s[14:15], 14
	s_and_b32 s0, s0, 0x3f00
	s_or_b32 s8, s8, s0
	s_lshl_b32 s0, s14, 8
	s_add_i32 s0, s0, 0x8000
	s_mul_i32 s4, s9, 0xc00
	s_mul_hi_u32 s12, s8, 0xc00
	s_bfe_u32 s36, s33, 0x30006
	s_ashr_i32 s1, s0, 31
	s_add_i32 s12, s12, s4
	s_mul_i32 s4, s8, 0xc00
	v_readlane_b32 s28, v242, 21
	v_readlane_b32 s29, v242, 22
	s_add_u32 s4, s28, s4
	s_addc_u32 s12, s29, s12
	s_mul_i32 s21, s36, 0x180
	s_add_u32 s28, s4, s21
	s_addc_u32 s29, s12, 0
	s_mul_i32 s12, s0, 0xc00
	s_mul_hi_i32 s4, s0, 0xc00
	s_add_u32 s12, s24, s12
	s_addc_u32 s4, s25, s4
	s_add_u32 s12, s12, s21
	s_addc_u32 s13, s4, 0
	s_mul_i32 s35, s14, 0x3000000
	s_mul_hi_i32 s4, s14, 0x3000000
	s_add_u32 s35, s24, s35
	s_addc_u32 s4, s25, s4
	s_add_u32 s38, s35, s21
	s_addc_u32 s39, s4, 0
	s_lshl_b64 s[0:1], s[0:1], 12
	s_add_u32 s0, s31, s0
	s_addc_u32 s1, s34, s1
	s_lshl_b32 s4, s36, 9
	s_add_u32 s0, s0, s4
	s_addc_u32 s1, s1, 0
	s_add_u32 s44, s0, 0x100
	s_addc_u32 s45, s1, 0
	s_lshl_b64 s[14:15], s[14:15], 26
	s_add_u32 s14, s31, s14
	s_addc_u32 s15, s34, s15
	s_add_u32 s4, s14, s4
	s_addc_u32 s14, s15, 0
	s_add_u32 s46, s4, 0x100
	v_readfirstlane_b32 s52, v0
	s_addc_u32 s47, s14, 0
	s_lshr_b32 s37, s52, 6
	s_lshl_b32 s35, s37, 5
	v_or_b32_e32 v4, s35, v165
	v_mov_b64_e32 v[2:3], s[28:29]
	v_mad_u64_u32 v[2:3], s[14:15], v4, s19, v[2:3]
	s_andn2_b32 s52, s52, 63
	v_lshl_add_u64 v[2:3], v[2:3], 0, v[148:149]
	global_load_dwordx4 v[142:145], v[2:3], off
	global_load_dwordx4 v[138:141], v[2:3], off offset:32
	global_load_dwordx4 v[134:137], v[2:3], off offset:64
	global_load_dwordx4 v[130:133], v[2:3], off offset:96
	global_load_dwordx4 v[126:129], v[2:3], off offset:128
	global_load_dwordx4 v[122:125], v[2:3], off offset:160
	global_load_dwordx4 v[118:121], v[2:3], off offset:192
	global_load_dwordx4 v[114:117], v[2:3], off offset:224
	global_load_dwordx4 v[110:113], v[2:3], off offset:256
	global_load_dwordx4 v[106:109], v[2:3], off offset:288
	global_load_dwordx4 v[102:105], v[2:3], off offset:320
	global_load_dwordx4 v[98:101], v[2:3], off offset:352
	v_or_b32_e32 v2, s52, v166
	v_mul_hi_i32 v3, v2, s20
	v_lshrrev_b32_e32 v4, 31, v3
	v_ashrrev_i32_e32 v3, 2, v3
	v_add_u32_e32 v3, v3, v4
	v_mul_lo_u32 v4, v3, 24
	v_sub_u32_e32 v4, v2, v4
	v_mul_lo_u32 v5, v3, s22
	v_lshrrev_b32_e32 v3, 1, v3
	v_bitop3_b32 v3, v3, v4, 7 bitop3:0x6c
	v_lshl_add_u32 v160, v3, 3, v5
	v_add_u32_e32 v3, 0x200, v2
	v_mul_hi_i32 v4, v3, s20
	v_lshrrev_b32_e32 v5, 31, v4
	v_ashrrev_i32_e32 v4, 2, v4
	v_add_u32_e32 v4, v4, v5
	v_mul_lo_u32 v5, v4, 24
	v_sub_u32_e32 v3, v3, v5
	v_mul_lo_u32 v5, v4, s22
	v_lshrrev_b32_e32 v4, 1, v4
	v_bitop3_b32 v3, v4, v3, 7 bitop3:0x6c
	v_lshl_add_u32 v162, v3, 3, v5
	v_add_u32_e32 v3, 0x400, v2
	v_mul_hi_i32 v4, v3, s20
	v_lshrrev_b32_e32 v5, 31, v4
	v_ashrrev_i32_e32 v4, 2, v4
	v_add_u32_e32 v4, v4, v5
	s_ashr_i32 s4, s52, 4
	v_mul_lo_u32 v5, v4, 24
	s_and_b32 s14, s4, 0x1ffff0
	s_lshr_b32 s4, s4, 1
	v_sub_u32_e32 v3, v3, v5
	v_mul_lo_u32 v5, v4, s22
	v_lshrrev_b32_e32 v4, 1, v4
	s_and_b32 s4, s4, 4
	v_bitop3_b32 v3, v4, v3, 7 bitop3:0x6c
	s_or_b32 s4, s14, s4
	v_lshl_add_u32 v168, v3, 3, v5
	v_or_b32_e32 v3, s4, v178
	s_add_i32 s4, s52, 0x200
	s_ashr_i32 s4, s4, 4
	s_and_b32 s14, s4, 0x1ffff0
	s_lshr_b32 s4, s4, 1
	s_and_b32 s4, s4, 4
	v_and_or_b32 v2, v2, s16, v177
	s_or_b32 s4, s14, s4
	v_lshl_or_b32 v170, v3, 11, v2
	v_or_b32_e32 v3, s4, v178
	s_lshl_b32 s4, s37, 10
	s_add_i32 s53, s4, 0
	v_ashrrev_i32_e32 v161, 31, v160
	v_lshl_or_b32 v172, v3, 11, v2
	s_add_i32 m0, s53, 0x8000
	v_lshl_add_u64 v[2:3], v[160:161], 1, s[12:13]
	v_ashrrev_i32_e32 v163, 31, v162
	global_load_lds_dwordx4 v[2:3], off
	v_lshl_add_u64 v[2:3], v[162:163], 1, s[12:13]
	s_add_i32 m0, s53, 0xa000
	v_ashrrev_i32_e32 v169, 31, v168
	global_load_lds_dwordx4 v[2:3], off
	v_lshl_add_u64 v[2:3], v[168:169], 1, s[12:13]
	s_add_i32 m0, s53, 0xc000
	v_ashrrev_i32_e32 v171, 31, v170
	global_load_lds_dwordx4 v[2:3], off
	v_lshl_add_u64 v[2:3], v[170:171], 1, s[0:1]
	v_lshl_add_u64 v[2:3], v[2:3], 0, s[6:7]
	s_mov_b32 m0, s53
	v_ashrrev_i32_e32 v173, 31, v172
	global_load_lds_dwordx4 v[2:3], off
	v_lshl_add_u64 v[2:3], v[172:173], 1, s[0:1]
	v_lshl_add_u64 v[2:3], v[2:3], 0, s[6:7]
	s_add_i32 m0, s53, 0x2000
	s_mov_b32 s4, -3
	global_load_lds_dwordx4 v[2:3], off
	s_waitcnt vmcnt(0)
	s_mov_b64 s[0:1], 64
	v_mov_b32_e32 v151, 0
	v_mov_b32_e32 v2, 0
	v_mov_b32_e32 v3, v147
	v_mov_b32_e32 v4, v147
	v_mov_b32_e32 v5, v147
	v_mov_b32_e32 v6, v147
	v_mov_b32_e32 v7, v147
	v_mov_b32_e32 v8, v147
	v_mov_b32_e32 v9, v147
	v_mov_b32_e32 v10, v147
	v_mov_b32_e32 v11, v147
	v_mov_b32_e32 v12, v147
	v_mov_b32_e32 v13, v147
	v_mov_b32_e32 v14, v147
	v_mov_b32_e32 v15, v147
	v_mov_b32_e32 v16, v147
	v_mov_b32_e32 v17, v147
	v_mov_b32_e32 v18, 0
	v_mov_b32_e32 v19, v147
	v_mov_b32_e32 v20, v147
	v_mov_b32_e32 v21, v147
	v_mov_b32_e32 v22, v147
	v_mov_b32_e32 v23, v147
	v_mov_b32_e32 v24, v147
	v_mov_b32_e32 v25, v147
	v_mov_b32_e32 v26, v147
	v_mov_b32_e32 v27, v147
	v_mov_b32_e32 v28, v147
	v_mov_b32_e32 v29, v147
	v_mov_b32_e32 v30, v147
	v_mov_b32_e32 v31, v147
	v_mov_b32_e32 v32, v147
	v_mov_b32_e32 v33, v147
	v_mov_b32_e32 v34, 0
	v_mov_b32_e32 v35, v147
	v_mov_b32_e32 v36, v147
	v_mov_b32_e32 v37, v147
	v_mov_b32_e32 v38, v147
	v_mov_b32_e32 v39, v147
	v_mov_b32_e32 v40, v147
	v_mov_b32_e32 v41, v147
	v_mov_b32_e32 v42, v147
	v_mov_b32_e32 v43, v147
	v_mov_b32_e32 v44, v147
	v_mov_b32_e32 v45, v147
	v_mov_b32_e32 v46, v147
	v_mov_b32_e32 v47, v147
	v_mov_b32_e32 v48, v147
	v_mov_b32_e32 v49, v147
	v_mov_b32_e32 v50, 0
	v_mov_b32_e32 v51, v147
	v_mov_b32_e32 v52, v147
	v_mov_b32_e32 v53, v147
	v_mov_b32_e32 v54, v147
	v_mov_b32_e32 v55, v147
	v_mov_b32_e32 v56, v147
	v_mov_b32_e32 v57, v147
	v_mov_b32_e32 v58, v147
	v_mov_b32_e32 v59, v147
	v_mov_b32_e32 v60, v147
	v_mov_b32_e32 v61, v147
	v_mov_b32_e32 v62, v147
	v_mov_b32_e32 v63, v147
	v_mov_b32_e32 v64, v147
	v_mov_b32_e32 v65, v147
	s_waitcnt vmcnt(0) lgkmcnt(0)
	s_barrier
	s_add_u32 s40, s12, 0x30000
	s_addc_u32 s41, s13, 0
	s_add_u32 s14, s44, 0x40000
	s_addc_u32 s15, s45, 0
	s_mov_b32 s98, 0
	s_mov_b32 s99, 0
	s_branch .LBB0_2312
.Lmla1_sw:
	s_mov_b32 s40, s38
	s_mov_b32 s41, s39
	s_mov_b32 s14, s46
	s_mov_b32 s15, s47
	s_branch .Lmla1_swr
.LBB0_2312:
	s_xor_b32 s42, s99, 0x6000
	s_add_i32 s42, s53, s42
	s_add_i32 m0, s42, 0x8000
	v_lshl_add_u64 v[66:67], v[160:161], 1, s[40:41]
	global_load_lds_dwordx4 v[66:67], off
	s_add_i32 m0, s42, 0xa000
	v_lshl_add_u64 v[66:67], v[162:163], 1, s[40:41]
	global_load_lds_dwordx4 v[66:67], off
	s_add_i32 m0, s42, 0xc000
	v_lshl_add_u64 v[66:67], v[168:169], 1, s[40:41]
	global_load_lds_dwordx4 v[66:67], off
	s_xor_b32 s42, s98, 0x4000
	s_add_i32 s42, s53, s42
	s_mov_b32 m0, s42
	v_lshl_add_u64 v[66:67], v[170:171], 1, s[14:15]
	global_load_lds_dwordx4 v[66:67], off
	s_add_i32 m0, s42, 0x2000
	v_lshl_add_u64 v[66:67], v[172:173], 1, s[14:15]
	global_load_lds_dwordx4 v[66:67], off
	s_add_u32 s40, s40, 0x30000
	s_addc_u32 s41, s41, 0
	s_add_u32 s14, s14, 0x40000
	s_addc_u32 s15, s15, 0
	s_cmpk_eq_i32 s0, 0xc0
	s_cbranch_scc1 .Lmla1_sw
	.Lmla1_swr:
	v_add_u32_e32 v74, s99, v182
	v_add_u32_e32 v75, v74, v181
	ds_read_b128 v[66:69], v75 offset:32768
	v_add_u32_e32 v76, v74, v183
	ds_read_b128 v[70:73], v76 offset:32768
	v_add_u32_e32 v153, v74, v184
	v_add_u32_e32 v155, v74, v185
	v_add_u32_e32 v157, v74, v186
	v_add_u32_e32 v159, v74, v187
	v_add_u32_e32 v209, v74, v188
	v_add_u32_e32 v218, v74, v189
	s_waitcnt lgkmcnt(0)
	v_mfma_f32_32x32x16_bf16 v[82:97], v[66:69], v[142:145], 0
	ds_read_b128 v[66:69], v153 offset:32768
	v_add_u32_e32 v219, v74, v190
	v_add_u32_e32 v220, v74, v191
	v_add_u32_e32 v221, v74, v192
	v_add_u32_e32 v222, v74, v193
	v_mfma_f32_32x32x16_bf16 v[82:97], v[70:73], v[138:141], v[82:97]
	ds_read_b128 v[70:73], v155 offset:32768
	s_waitcnt lgkmcnt(0)
	v_mfma_f32_32x32x16_bf16 v[82:97], v[66:69], v[134:137], v[82:97]
	ds_read_b128 v[66:69], v157 offset:32768
	v_mfma_f32_32x32x16_bf16 v[82:97], v[70:73], v[130:133], v[82:97]
	ds_read_b128 v[70:73], v159 offset:32768
	s_waitcnt lgkmcnt(0)
	v_mfma_f32_32x32x16_bf16 v[82:97], v[66:69], v[126:129], v[82:97]
	ds_read_b128 v[66:69], v209 offset:32768
	v_mfma_f32_32x32x16_bf16 v[82:97], v[70:73], v[122:125], v[82:97]
	ds_read_b128 v[70:73], v218 offset:32768
	s_waitcnt lgkmcnt(0)
	v_mfma_f32_32x32x16_bf16 v[82:97], v[66:69], v[118:121], v[82:97]
	ds_read_b128 v[66:69], v219 offset:32768
	v_mfma_f32_32x32x16_bf16 v[82:97], v[70:73], v[114:117], v[82:97]
	ds_read_b128 v[70:73], v220 offset:32768
	s_waitcnt lgkmcnt(0)
	v_mfma_f32_32x32x16_bf16 v[82:97], v[66:69], v[110:113], v[82:97]
	ds_read_b128 v[66:69], v221 offset:32768
	v_mfma_f32_32x32x16_bf16 v[82:97], v[70:73], v[106:109], v[82:97]
	ds_read_b128 v[70:73], v222 offset:32768
	s_waitcnt lgkmcnt(0)
	v_mfma_f32_32x32x16_bf16 v[82:97], v[66:69], v[102:105], v[82:97]
	v_mfma_f32_32x32x16_bf16 v[82:97], v[70:73], v[98:101], v[82:97]
	ds_read_b128 v[66:69], v75 offset:45056
	ds_read_b128 v[210:213], v76 offset:45056
	s_nop 9
	v_exp_f32_e32 v226, v86
	v_exp_f32_e32 v227, v87
	v_exp_f32_e32 v228, v88
	s_waitcnt lgkmcnt(0)
	v_mfma_f32_32x32x16_bf16 v[66:81], v[66:69], v[142:145], 0
	v_exp_f32_e32 v229, v89
	v_exp_f32_e32 v230, v90
	v_exp_f32_e32 v231, v91
	v_exp_f32_e32 v232, v92
	v_exp_f32_e32 v233, v93
	v_exp_f32_e32 v234, v94
	v_exp_f32_e32 v235, v95
	v_mfma_f32_32x32x16_bf16 v[66:81], v[210:213], v[138:141], v[66:81]
	ds_read_b128 v[210:213], v153 offset:45056
	ds_read_b128 v[214:217], v155 offset:45056
	v_exp_f32_e32 v238, v82
	v_exp_f32_e32 v236, v96
	v_exp_f32_e32 v237, v97
	v_cvt_pk_bf16_f32 v86, v230, v231
	v_cvt_pk_bf16_f32 v87, v232, v233
	v_cvt_pk_bf16_f32 v88, v234, v235
	s_waitcnt lgkmcnt(0)
	v_mfma_f32_32x32x16_bf16 v[66:81], v[210:213], v[134:137], v[66:81]
	v_cvt_pk_bf16_f32 v89, v236, v237
	v_add_u32_e32 v153, s98, v179
	v_permlane32_swap_b32_e32 v86, v88
	v_permlane32_swap_b32_e32 v87, v89
	v_mfma_f32_32x32x16_bf16 v[66:81], v[214:217], v[130:133], v[66:81]
	ds_read_b128 v[210:213], v157 offset:45056
	ds_read_b128 v[214:217], v159 offset:45056
	v_exp_f32_e32 v239, v83
	v_exp_f32_e32 v240, v84
	v_cvt_pk_bf16_f32 v84, v226, v227
	v_cvt_pk_bf16_f32 v82, v238, v239
	s_nop 1
	v_permlane32_swap_b32_e32 v82, v84
	s_waitcnt lgkmcnt(0)
	v_mfma_f32_32x32x16_bf16 v[66:81], v[210:213], v[126:129], v[66:81]
	v_mfma_f32_32x32x16_bf16 v[66:81], v[214:217], v[122:125], v[66:81]
	ds_read_b128 v[210:213], v209 offset:45056
	ds_read_b128 v[214:217], v218 offset:45056
	v_exp_f32_e32 v241, v85
	v_cvt_pk_bf16_f32 v85, v228, v229
	v_cvt_pk_bf16_f32 v83, v240, v241
	s_nop 1
	v_permlane32_swap_b32_e32 v83, v85
	s_waitcnt lgkmcnt(0)
	v_mfma_f32_32x32x16_bf16 v[66:81], v[210:213], v[118:121], v[66:81]
	ds_read_b128 v[210:213], v219 offset:45056
	v_mfma_f32_32x32x16_bf16 v[66:81], v[214:217], v[114:117], v[66:81]
	ds_read_b128 v[214:217], v220 offset:45056
	ds_read_b128 v[218:221], v221 offset:45056
	ds_read_b128 v[222:225], v222 offset:45056
	s_waitcnt lgkmcnt(0)
	v_mfma_f32_32x32x16_bf16 v[66:81], v[210:213], v[110:113], v[66:81]
	v_mfma_f32_32x32x16_bf16 v[66:81], v[214:217], v[106:109], v[66:81]
	v_mfma_f32_32x32x16_bf16 v[66:81], v[218:221], v[102:105], v[66:81]
	v_mfma_f32_32x32x16_bf16 v[66:81], v[222:225], v[98:101], v[66:81]
	ds_read_b64_tr_b16 v[90:91], v153 offset:0
	ds_read_b64_tr_b16 v[92:93], v153 offset:0x800
	ds_read_b64_tr_b16 v[94:95], v153 offset:0x1000
	ds_read_b64_tr_b16 v[96:97], v153 offset:0x1800
	ds_read_b64_tr_b16 v[210:211], v153 offset:0x200
	ds_read_b64_tr_b16 v[212:213], v153 offset:0xa00
	ds_read_b64_tr_b16 v[214:215], v153 offset:0x1200
	ds_read_b64_tr_b16 v[216:217], v153 offset:0x1a00
	s_waitcnt lgkmcnt(4)
	s_nop 0
	v_mfma_f32_32x32x16_bf16 v[2:17], v[82:85], v[90:93], v[2:17]
	s_nop 9
	v_exp_f32_e32 v218, v66
	v_exp_f32_e32 v219, v67
	v_exp_f32_e32 v220, v68
	v_exp_f32_e32 v221, v69
	v_mfma_f32_32x32x16_bf16 v[2:17], v[86:89], v[94:97], v[2:17]
	ds_read_b64_tr_b16 v[66:67], v153 offset:0x400
	ds_read_b64_tr_b16 v[68:69], v153 offset:0xc00
	ds_read_b64_tr_b16 v[90:91], v153 offset:0x1400
	ds_read_b64_tr_b16 v[92:93], v153 offset:0x1c00
	s_waitcnt lgkmcnt(4)
	v_mfma_f32_32x32x16_bf16 v[18:33], v[82:85], v[210:213], v[18:33]
	v_exp_f32_e32 v210, v70
	v_exp_f32_e32 v211, v71
	v_exp_f32_e32 v212, v72
	v_exp_f32_e32 v213, v73
	v_mfma_f32_32x32x16_bf16 v[18:33], v[86:89], v[214:217], v[18:33]
	ds_read_b64_tr_b16 v[70:71], v153 offset:0x600
	ds_read_b64_tr_b16 v[72:73], v153 offset:0xe00
	ds_read_b64_tr_b16 v[94:95], v153 offset:0x1600
	ds_read_b64_tr_b16 v[96:97], v153 offset:0x1e00
	s_waitcnt lgkmcnt(4)
	v_mfma_f32_32x32x16_bf16 v[34:49], v[82:85], v[66:69], v[34:49]
	v_exp_f32_e32 v214, v74
	v_exp_f32_e32 v215, v75
	v_exp_f32_e32 v216, v76
	v_exp_f32_e32 v217, v77
	v_mfma_f32_32x32x16_bf16 v[34:49], v[86:89], v[90:93], v[34:49]
	ds_read_b64_tr_b16 v[66:67], v153 offset:0x2000
	ds_read_b64_tr_b16 v[68:69], v153 offset:0x2800
	ds_read_b64_tr_b16 v[74:75], v153 offset:0x3000
	ds_read_b64_tr_b16 v[76:77], v153 offset:0x3800
	s_waitcnt lgkmcnt(4)
	v_exp_f32_e32 v90, v78
	v_mfma_f32_32x32x16_bf16 v[50:65], v[82:85], v[70:73], v[50:65]
	v_exp_f32_e32 v91, v79
	v_cvt_pk_bf16_f32 v72, v210, v211
	v_cvt_pk_bf16_f32 v73, v212, v213
	v_mfma_f32_32x32x16_bf16 v[50:65], v[86:89], v[94:97], v[50:65]
	v_exp_f32_e32 v252, v80
	v_exp_f32_e32 v253, v81
	v_cvt_pk_bf16_f32 v78, v214, v215
	v_cvt_pk_bf16_f32 v79, v216, v217
	v_cvt_pk_bf16_f32 v80, v90, v91
	v_cvt_pk_bf16_f32 v70, v218, v219
	v_cvt_pk_bf16_f32 v71, v220, v221
	v_permlane32_swap_b32_e32 v78, v80
	v_cvt_pk_bf16_f32 v81, v252, v253
	v_permlane32_swap_b32_e32 v70, v72
	v_permlane32_swap_b32_e32 v71, v73
	s_nop 0
	v_permlane32_swap_b32_e32 v79, v81
	ds_read_b64_tr_b16 v[82:83], v153 offset:0x2200
	ds_read_b64_tr_b16 v[84:85], v153 offset:0x2a00
	ds_read_b64_tr_b16 v[86:87], v153 offset:0x3200
	ds_read_b64_tr_b16 v[88:89], v153 offset:0x3a00
	s_waitcnt lgkmcnt(4)
	s_nop 0
	v_mfma_f32_32x32x16_bf16 v[2:17], v[70:73], v[66:69], v[2:17]
	v_pk_add_f32 v[246:247], v[238:239], v[240:241]
	v_pk_add_f32 v[246:247], v[246:247], v[226:227]
	v_mfma_f32_32x32x16_bf16 v[2:17], v[78:81], v[74:77], v[2:17]
	v_pk_add_f32 v[246:247], v[246:247], v[228:229]
	v_pk_add_f32 v[246:247], v[246:247], v[230:231]
	ds_read_b64_tr_b16 v[66:67], v153 offset:0x2400
	ds_read_b64_tr_b16 v[68:69], v153 offset:0x2c00
	ds_read_b64_tr_b16 v[74:75], v153 offset:0x3400
	ds_read_b64_tr_b16 v[76:77], v153 offset:0x3c00
	s_waitcnt lgkmcnt(4)
	v_mfma_f32_32x32x16_bf16 v[18:33], v[70:73], v[82:85], v[18:33]
	v_pk_add_f32 v[246:247], v[246:247], v[232:233]
	v_pk_add_f32 v[246:247], v[246:247], v[234:235]
	v_mfma_f32_32x32x16_bf16 v[18:33], v[78:81], v[86:89], v[18:33]
	v_pk_add_f32 v[246:247], v[246:247], v[236:237]
	v_pk_add_f32 v[246:247], v[246:247], v[218:219]
	ds_read_b64_tr_b16 v[82:83], v153 offset:0x2600
	ds_read_b64_tr_b16 v[84:85], v153 offset:0x2e00
	ds_read_b64_tr_b16 v[86:87], v153 offset:0x3600
	ds_read_b64_tr_b16 v[88:89], v153 offset:0x3e00
	s_waitcnt lgkmcnt(4)
	v_mfma_f32_32x32x16_bf16 v[34:49], v[70:73], v[66:69], v[34:49]
	v_pk_add_f32 v[246:247], v[246:247], v[220:221]
	v_pk_add_f32 v[246:247], v[246:247], v[210:211]
	v_mfma_f32_32x32x16_bf16 v[34:49], v[78:81], v[74:77], v[34:49]
	v_pk_add_f32 v[246:247], v[246:247], v[212:213]
	v_pk_add_f32 v[246:247], v[246:247], v[214:215]
	s_waitcnt lgkmcnt(0)
	v_mfma_f32_32x32x16_bf16 v[50:65], v[70:73], v[82:85], v[50:65]
	v_pk_add_f32 v[246:247], v[246:247], v[216:217]
	v_pk_add_f32 v[246:247], v[246:247], v[90:91]
	v_pk_add_f32 v[246:247], v[246:247], v[252:253]
	v_add_f32_e32 v246, v246, v247
	v_mov_b32_e32 v247, v246
	s_nop 1
	v_permlane32_swap_b32_e32 v246, v247
	v_add_f32_e32 v246, v246, v247
	v_add_f32_e32 v151, v151, v246
	s_waitcnt vmcnt(0)
	s_add_u32 s0, s0, 64
	s_xor_b32 s99, s99, 0x6000
	s_xor_b32 s98, s98, 0x4000
	s_cmpk_eq_i32 s0, 0x4100
	s_waitcnt vmcnt(0)
	s_barrier
	v_mfma_f32_32x32x16_bf16 v[50:65], v[78:81], v[86:89], v[50:65]
	s_cbranch_scc0 .LBB0_2312
	s_lshl_b32 s0, s52, 2
	s_add_i32 s4, s0, 0
	s_add_i32 s4, s4, 0x1e000
	ds_read_b128 v[66:69], v196
	ds_read_b128 v[70:73], v197
	s_waitcnt lgkmcnt(1)
	v_mfma_f32_32x32x16_bf16 v[82:97], v[66:69], v[142:145], 0
	s_waitcnt lgkmcnt(0)
	v_mfma_f32_32x32x16_bf16 v[82:97], v[70:73], v[138:141], v[82:97]
	ds_read_b128 v[66:69], v198
	ds_read_b128 v[70:73], v199
	s_waitcnt lgkmcnt(1)
	v_mfma_f32_32x32x16_bf16 v[82:97], v[66:69], v[134:137], v[82:97]
	s_waitcnt lgkmcnt(0)
	v_mfma_f32_32x32x16_bf16 v[82:97], v[70:73], v[130:133], v[82:97]
	ds_read_b128 v[66:69], v200
	ds_read_b128 v[70:73], v201
	s_waitcnt lgkmcnt(1)
	v_mfma_f32_32x32x16_bf16 v[82:97], v[66:69], v[126:129], v[82:97]
	s_waitcnt lgkmcnt(0)
	v_mfma_f32_32x32x16_bf16 v[82:97], v[70:73], v[122:125], v[82:97]
	ds_read_b128 v[66:69], v202
	ds_read_b128 v[70:73], v203
	s_waitcnt lgkmcnt(1)
	v_mfma_f32_32x32x16_bf16 v[82:97], v[66:69], v[118:121], v[82:97]
	s_waitcnt lgkmcnt(0)
	v_mfma_f32_32x32x16_bf16 v[82:97], v[70:73], v[114:117], v[82:97]
	ds_read_b128 v[66:69], v204
	ds_read_b128 v[70:73], v205
	s_waitcnt lgkmcnt(1)
	v_mfma_f32_32x32x16_bf16 v[82:97], v[66:69], v[110:113], v[82:97]
	s_waitcnt lgkmcnt(0)
	v_mfma_f32_32x32x16_bf16 v[82:97], v[70:73], v[106:109], v[82:97]
	ds_read_b128 v[66:69], v206
	ds_read_b128 v[70:73], v207
	s_waitcnt lgkmcnt(1)
	v_mfma_f32_32x32x16_bf16 v[82:97], v[66:69], v[102:105], v[82:97]
	s_waitcnt lgkmcnt(0)
	v_mfma_f32_32x32x16_bf16 v[82:97], v[70:73], v[98:101], v[82:97]
	ds_read_b128 v[66:69], v196 offset:12288
	ds_read_b128 v[160:163], v197 offset:12288
	s_waitcnt lgkmcnt(1)
	v_mfma_f32_32x32x16_bf16 v[66:81], v[66:69], v[142:145], 0
	s_waitcnt lgkmcnt(0)
	v_mfma_f32_32x32x16_bf16 v[66:81], v[160:163], v[138:141], v[66:81]
	ds_read_b128 v[138:141], v198 offset:12288
	ds_read_b128 v[142:145], v199 offset:12288
	s_waitcnt lgkmcnt(1)
	v_mfma_f32_32x32x16_bf16 v[66:81], v[138:141], v[134:137], v[66:81]
	s_waitcnt lgkmcnt(0)
	v_mfma_f32_32x32x16_bf16 v[66:81], v[142:145], v[130:133], v[66:81]
	ds_read_b128 v[130:133], v200 offset:12288
	ds_read_b128 v[134:137], v201 offset:12288
	s_waitcnt lgkmcnt(1)
	v_mfma_f32_32x32x16_bf16 v[66:81], v[130:133], v[126:129], v[66:81]
	v_exp_f32_e32 v130, v82
	v_exp_f32_e32 v131, v83
	v_exp_f32_e32 v132, v84
	v_cvt_pk_bf16_f32 v82, v130, v131
	s_waitcnt lgkmcnt(0)
	v_mfma_f32_32x32x16_bf16 v[66:81], v[134:137], v[122:125], v[66:81]
	ds_read_b128 v[122:125], v202 offset:12288
	ds_read_b128 v[126:129], v203 offset:12288
	s_waitcnt lgkmcnt(1)
	v_mfma_f32_32x32x16_bf16 v[66:81], v[122:125], v[118:121], v[66:81]
	s_waitcnt lgkmcnt(0)
	v_mfma_f32_32x32x16_bf16 v[66:81], v[126:129], v[114:117], v[66:81]
	ds_read_b128 v[114:117], v204 offset:12288
	ds_read_b128 v[118:121], v205 offset:12288
	ds_read_b128 v[122:125], v206 offset:12288
	ds_read_b128 v[126:129], v207 offset:12288
	s_waitcnt lgkmcnt(3)
	v_mfma_f32_32x32x16_bf16 v[66:81], v[114:117], v[110:113], v[66:81]
	v_exp_f32_e32 v110, v85
	v_exp_f32_e32 v111, v86
	v_exp_f32_e32 v112, v87
	v_exp_f32_e32 v113, v88
	v_exp_f32_e32 v114, v89
	v_exp_f32_e32 v115, v90
	v_exp_f32_e32 v116, v91
	s_waitcnt lgkmcnt(2)
	v_mfma_f32_32x32x16_bf16 v[66:81], v[118:121], v[106:109], v[66:81]
	v_exp_f32_e32 v106, v92
	v_exp_f32_e32 v107, v93
	v_exp_f32_e32 v108, v94
	v_exp_f32_e32 v109, v95
	v_exp_f32_e32 v117, v96
	v_exp_f32_e32 v118, v97
	v_cvt_pk_bf16_f32 v83, v132, v110
	s_waitcnt lgkmcnt(1)
	v_mfma_f32_32x32x16_bf16 v[66:81], v[122:125], v[102:105], v[66:81]
	v_cvt_pk_bf16_f32 v84, v111, v112
	v_cvt_pk_bf16_f32 v85, v113, v114
	v_cvt_pk_bf16_f32 v86, v115, v116
	v_cvt_pk_bf16_f32 v87, v106, v107
	v_cvt_pk_bf16_f32 v88, v108, v109
	v_cvt_pk_bf16_f32 v89, v117, v118
	v_permlane32_swap_b32_e32 v82, v84
	s_waitcnt lgkmcnt(0)
	v_mfma_f32_32x32x16_bf16 v[66:81], v[126:129], v[98:101], v[66:81]
	v_permlane32_swap_b32_e32 v83, v85
	v_permlane32_swap_b32_e32 v86, v88
	v_permlane32_swap_b32_e32 v87, v89
	ds_read_b64_tr_b16 v[90:91], v208 offset:0
	ds_read_b64_tr_b16 v[92:93], v208 offset:0x800
	ds_read_b64_tr_b16 v[94:95], v208 offset:0x1000
	ds_read_b64_tr_b16 v[96:97], v208 offset:0x1800
	ds_read_b64_tr_b16 v[98:99], v208 offset:0x200
	ds_read_b64_tr_b16 v[100:101], v208 offset:0xa00
	ds_read_b64_tr_b16 v[102:103], v208 offset:0x1200
	ds_read_b64_tr_b16 v[104:105], v208 offset:0x1a00
	s_waitcnt lgkmcnt(4)
	s_nop 0
	v_mfma_f32_32x32x16_bf16 v[2:17], v[82:85], v[90:93], v[2:17]
	s_nop 6
	v_exp_f32_e32 v119, v66
	v_exp_f32_e32 v120, v67
	v_exp_f32_e32 v121, v68
	v_exp_f32_e32 v122, v69
	v_mfma_f32_32x32x16_bf16 v[2:17], v[86:89], v[94:97], v[2:17]
	ds_read_b64_tr_b16 v[66:67], v208 offset:0x400
	ds_read_b64_tr_b16 v[68:69], v208 offset:0xc00
	ds_read_b64_tr_b16 v[90:91], v208 offset:0x1400
	ds_read_b64_tr_b16 v[92:93], v208 offset:0x1c00
	s_waitcnt lgkmcnt(4)
	v_mfma_f32_32x32x16_bf16 v[18:33], v[82:85], v[98:101], v[18:33]
	v_exp_f32_e32 v98, v70
	v_exp_f32_e32 v99, v71
	v_exp_f32_e32 v100, v72
	v_exp_f32_e32 v101, v73
	v_mfma_f32_32x32x16_bf16 v[18:33], v[86:89], v[102:105], v[18:33]
	ds_read_b64_tr_b16 v[70:71], v208 offset:0x600
	ds_read_b64_tr_b16 v[72:73], v208 offset:0xe00
	ds_read_b64_tr_b16 v[94:95], v208 offset:0x1600
	ds_read_b64_tr_b16 v[96:97], v208 offset:0x1e00
	s_waitcnt lgkmcnt(4)
	v_mfma_f32_32x32x16_bf16 v[34:49], v[82:85], v[66:69], v[34:49]
	v_exp_f32_e32 v102, v74
	v_exp_f32_e32 v103, v75
	v_exp_f32_e32 v104, v76
	v_exp_f32_e32 v105, v77
	v_mfma_f32_32x32x16_bf16 v[34:49], v[86:89], v[90:93], v[34:49]
	ds_read_b64_tr_b16 v[74:75], v208 offset:0x2000
	ds_read_b64_tr_b16 v[76:77], v208 offset:0x2800
	ds_read_b64_tr_b16 v[90:91], v208 offset:0x3000
	ds_read_b64_tr_b16 v[92:93], v208 offset:0x3800
	s_waitcnt lgkmcnt(4)
	v_add_f32_e32 v66, v130, v131
	v_add_f32_e32 v67, v119, v120
	v_mfma_f32_32x32x16_bf16 v[50:65], v[82:85], v[70:73], v[50:65]
	v_add_f32_e32 v66, v66, v132
	v_add_f32_e32 v67, v67, v121
	v_exp_f32_e32 v123, v78
	v_add_f32_e32 v66, v66, v110
	v_add_f32_e32 v67, v67, v122
	v_exp_f32_e32 v124, v79
	v_add_f32_e32 v66, v66, v111
	v_add_f32_e32 v67, v67, v98
	v_mfma_f32_32x32x16_bf16 v[50:65], v[86:89], v[94:97], v[50:65]
	v_add_f32_e32 v66, v66, v112
	v_add_f32_e32 v67, v67, v99
	v_exp_f32_e32 v125, v80
	v_add_f32_e32 v66, v66, v113
	v_add_f32_e32 v67, v67, v100
	v_exp_f32_e32 v81, v81
	v_add_f32_e32 v66, v66, v114
	v_add_f32_e32 v67, v67, v101
	v_cvt_pk_bf16_f32 v68, v119, v120
	v_add_f32_e32 v66, v66, v115
	v_add_f32_e32 v67, v67, v102
	v_cvt_pk_bf16_f32 v69, v121, v122
	v_add_f32_e32 v66, v66, v116
	v_add_f32_e32 v67, v67, v103
	v_cvt_pk_bf16_f32 v70, v98, v99
	v_add_f32_e32 v66, v66, v106
	v_add_f32_e32 v67, v67, v104
	v_cvt_pk_bf16_f32 v71, v100, v101
	v_add_f32_e32 v66, v66, v107
	v_add_f32_e32 v67, v67, v105
	v_cvt_pk_bf16_f32 v78, v102, v103
	v_add_f32_e32 v66, v66, v108
	v_add_f32_e32 v67, v67, v123
	v_cvt_pk_bf16_f32 v79, v104, v105
	v_add_f32_e32 v66, v66, v109
	v_add_f32_e32 v67, v67, v124
	v_cvt_pk_bf16_f32 v80, v123, v124
	v_add_f32_e32 v66, v66, v117
	v_add_f32_e32 v67, v67, v125
	v_permlane32_swap_b32_e32 v68, v70
	v_add_f32_e32 v66, v66, v118
	v_add_f32_e32 v67, v67, v81
	v_cvt_pk_bf16_f32 v81, v125, v81
	v_add_f32_e32 v66, v66, v67
	v_mov_b32_e32 v67, v66
	s_nop 1
	v_permlane32_swap_b32_e32 v66, v67
	v_permlane32_swap_b32_e32 v69, v71
	v_permlane32_swap_b32_e32 v78, v80
	v_permlane32_swap_b32_e32 v79, v81
	ds_read_b64_tr_b16 v[82:83], v208 offset:0x2200
	ds_read_b64_tr_b16 v[84:85], v208 offset:0x2a00
	ds_read_b64_tr_b16 v[86:87], v208 offset:0x3200
	ds_read_b64_tr_b16 v[88:89], v208 offset:0x3a00
	s_waitcnt lgkmcnt(4)
	v_mfma_f32_32x32x16_bf16 v[2:17], v[68:71], v[74:77], v[2:17]
	s_nop 0
	v_mfma_f32_32x32x16_bf16 v[2:17], v[78:81], v[90:93], v[2:17]
	ds_read_b64_tr_b16 v[72:73], v208 offset:0x2400
	ds_read_b64_tr_b16 v[74:75], v208 offset:0x2c00
	ds_read_b64_tr_b16 v[90:91], v208 offset:0x3400
	ds_read_b64_tr_b16 v[92:93], v208 offset:0x3c00
	s_waitcnt lgkmcnt(4)
	v_mfma_f32_32x32x16_bf16 v[18:33], v[68:71], v[82:85], v[18:33]
	v_mfma_f32_32x32x16_bf16 v[18:33], v[78:81], v[86:89], v[18:33]
	ds_read_b64_tr_b16 v[82:83], v208 offset:0x2600
	ds_read_b64_tr_b16 v[84:85], v208 offset:0x2e00
	ds_read_b64_tr_b16 v[86:87], v208 offset:0x3600
	ds_read_b64_tr_b16 v[88:89], v208 offset:0x3e00
	s_waitcnt lgkmcnt(4)
	v_mfma_f32_32x32x16_bf16 v[34:49], v[68:71], v[72:75], v[34:49]
	v_mfma_f32_32x32x16_bf16 v[34:49], v[78:81], v[90:93], v[34:49]
	s_waitcnt lgkmcnt(0)
	v_mfma_f32_32x32x16_bf16 v[50:65], v[68:71], v[82:85], v[50:65]
	s_waitcnt vmcnt(0)
	s_barrier
	v_mfma_f32_32x32x16_bf16 v[50:65], v[78:81], v[86:89], v[50:65]
	s_and_saveexec_b64 s[0:1], s[2:3]
	s_cbranch_execz .LBB0_2310
	v_add_f32_e32 v66, v66, v67
	v_lshl_add_u32 v68, v165, 2, s4
	v_add_f32_e32 v66, v151, v66
	ds_write_b32 v68, v66
	s_branch .LBB0_2310
